# sample attention items, selected branch: page-table lookup and K/V pointer arithmetic of the tile parameter block skipped for tiles i > 0 (result only used at i == 0), on top of v019
# speedup vs baseline: 1.0032x; 1.0008x over previous
; __device__ __forceinline__ void attn_item(const P& p, Frame& F, const bool is_s, const int b, const int g, const int c) {
;     ...
;                 else { const int j = UL[i], msk = UM[i]; kp0 = 64 * j; pitch = 1024; lv = qvalid && ((msk >> (ql & 3)) & 1);
;                     if (j < 128) { const int page = pt[j >> 1]; const float* kb = ckv + ((size_t)(page * PAGE + (j & 1) * 64) * 4 + 2) * 256 + g * 128; kp = kb; vp = kb + 256; mode = 1; }
;                     else { const bf16* kb = KVN + (size_t)(MP + b * 4) * 1024 + 2 * 256 + g * 128; kp = kb; vp = kb + 256; nvalid = 4; } }
;     ...
;                 if (i == 0) { __syncthreads(); if (loader) loader_stage(F, kp, vp, pitch, mode == 1, nvalid, tid - 256, 0); }
.LBB0_2031:
	s_or_b64 exec, exec, s[0:1]
	s_movk_i32 s0, 0x7f
	s_waitcnt lgkmcnt(0)
	v_cmp_lt_i32_e32 vcc, s0, v2
	v_lshlrev_b32_e32 v1, 6, v2
	s_mov_b32 s84, 4
	v_mov_b64_e32 v[98:99], s[34:35]
	v_mov_b64_e32 v[16:17], s[36:37]
	s_cbranch_vccnz .LBB0_2033
	s_cmp_lg_u32 s33, 0
	s_cbranch_scc1 .Lattn_skip_pt
	v_ashrrev_i32_e32 v4, 1, v2
	v_ashrrev_i32_e32 v5, 31, v4
	v_lshlrev_b64 v[4:5], 2, v[4:5]
	v_lshl_add_u64 v[4:5], s[76:77], 0, v[4:5]
	global_load_dword v2, v[4:5], off
	v_and_b32_e32 v4, 64, v1
	s_mov_b64 s[0:1], 0x800
	s_mov_b32 s84, 64
	s_mov_b64 s[14:15], -1
	s_waitcnt vmcnt(0)
	v_lshlrev_b32_e32 v2, 7, v2
	v_or_b32_e32 v4, v2, v4
	v_ashrrev_i32_e32 v5, 31, v4
	v_lshlrev_b64 v[4:5], 12, v[4:5]
	v_lshl_add_u64 v[4:5], s[38:39], 0, v[4:5]
	v_lshl_add_u64 v[98:99], v[4:5], 0, s[0:1]
	s_mov_b64 s[0:1], 0xc00
	v_lshl_add_u64 v[16:17], v[4:5], 0, s[0:1]
	s_branch .LBB0_2033
.Lattn_skip_pt:
	s_mov_b32 s84, 64
	s_mov_b64 s[14:15], -1
	s_mov_b64 s[0:1], 0xc00
